# adds: in the mixer phase waves 0-3 run the conv/pool unit before their attention units and waves 4-7 after, so each SIMD overlaps one wave's latency-bound conv/pool with its partner's VALU-bound atten
# baseline (speedup 1.0000x reference)
; #define PG8_STAGE(bufoff, gbase, voff) do { _Pragma("unroll") for (int _i = 0; _i < 2; ++_i) \
;         __builtin_amdgcn_global_load_lds((const unsigned*)((const char*)(gbase) + (voff)[_i]), (LAS unsigned*)(lds + (bufoff) + ldsw + _i * 8192), 16, 0, 0); } while (0)
; #define PG8_WAIT_V(n) asm volatile("s_waitcnt vmcnt(" #n ")" ::: "memory")
; #define PG8_BAR __builtin_amdgcn_s_barrier()
; template <class Epi, class Sched>
; __device__ __forceinline__ void gemm_phase(LAS unsigned char* lds, const Gemm g, const Sched& S, const Epi& E, const int tid) {
;     ...
;     for (int i = 0; i < 2; ++i) { int R, C; stage_rc(tid * 16 + i * 8192, R, C); const int Rb = Epi::PERM ? ((R & ~31) + perm32(R & 31)) : R;
;         voffA[i] = (unsigned)(R * K + C) * 2u; voffB[i] = (unsigned)(Rb * K + C) * 2u; }
;     const size_t kstep = (size_t)(BK * 2);
;     const size_t hstep = (size_t)HALF * K * 2;
;     const size_t tstep = 2 * hstep;
;     const unsigned ldsw = (unsigned)wid * 1024u;
;     const int aoff = lds_byte(wr * 64 + fr, fq * 8), boff = lds_byte(wc * 32 + fr, fq * 8);
;     ...
;     PG8_STAGE(PG8_SB(0, 0), cB, voffB); PG8_STAGE(PG8_SB(0, 1), cB + hstep, voffB); PG8_STAGE(PG8_SA(0, 0), cA, voffA); PG8_STAGE(PG8_SA(0, 1), cA + hstep, voffA);
;     if (wr == 1) PG8_BAR;
;     PG8_WAIT_V(2); PG8_BAR;
;     PG8_STAGE(PG8_SB(1, 0), cB + kstep, voffB); PG8_STAGE(PG8_SA(1, 0), cA + kstep, voffA); PG8_STAGE(PG8_SB(1, 1), cB + hstep + kstep, voffB);
;     PG8_WAIT_V(6); PG8_BAR;
.LBB0_160:
	s_and_b64 s[4:5], s[4:5], exec
	s_cselect_b32 s4, 0x8000, 0
	v_readlane_b32 s3, v254, 54
	s_add_u32 s91, s3, s4
	v_readlane_b32 s3, v254, 56
	s_addc_u32 s92, s3, 0
	v_readlane_b32 s64, v252, 63
	s_add_u32 s4, s66, 0x40080
	v_mov_b32_e32 v139, v193
	v_readlane_b32 s65, v253, 0
	v_lshl_add_u64 v[0:1], v[0:1], 0, s[68:69]
	s_addc_u32 s5, s67, 0
	s_add_i32 m0, s75, 0x18000
	v_mov_b32_e32 v137, v193
	v_lshl_add_u64 v[10:11], s[64:65], 0, v[138:139]
	v_lshl_add_u64 v[2:3], v[2:3], 0, s[68:69]
	s_waitcnt vmcnt(2)
	s_barrier
	global_load_lds_dwordx4 v[0:1], off
	s_add_i32 m0, s75, 0x1a000
	s_add_i32 s93, s75, 0x8000
	v_lshl_add_u64 v[12:13], s[64:65], 0, v[136:137]
	v_and_b32_e32 v18, 15, v132
	v_lshrrev_b32_e32 v14, 1, v132
	v_lshl_add_u64 v[10:11], v[10:11], 0, s[68:69]
	global_load_lds_dwordx4 v[2:3], off
	s_mov_b32 m0, s93
	s_add_i32 s94, s75, 0xa000
	v_and_b32_e32 v19, 24, v14
	v_lshlrev_b32_e32 v14, 6, v18
	v_lshl_add_u64 v[12:13], v[12:13], 0, s[68:69]
	global_load_lds_dwordx4 v[10:11], off
	s_mov_b32 m0, s94
	s_nop 0
	v_lshl_or_b32 v20, v19, 1, v14
	v_lshl_add_u64 v[14:15], s[4:5], 0, v[192:193]
	global_load_lds_dwordx4 v[12:13], off
	s_add_i32 m0, s75, 0x1c000
	v_lshl_add_u64 v[16:17], s[4:5], 0, v[134:135]
	global_load_lds_dwordx4 v[14:15], off
	s_add_i32 m0, s75, 0x1e000
	v_lshlrev_b32_e32 v0, 14, v8
	global_load_lds_dwordx4 v[16:17], off
	s_lshl_b32 s22, s22, 5
	v_and_b32_e32 v0, 0xffff8000, v0
	v_lshlrev_b32_e32 v21, 2, v18
	s_and_b32 s22, s22, 0x60
	v_lshl_add_u32 v0, v7, 11, v0
	v_and_b32_e32 v1, 1, v8
	v_and_b32_e32 v22, 32, v21
	s_lshl_b32 s23, s22, 2
	s_lshl_b32 s38, s7, 8
	s_waitcnt lgkmcnt(0)
	v_lshl_or_b32 v165, s7, 6, v18
	s_lshl_b32 s7, s7, 13
	v_lshl_or_b32 v0, v1, 6, v0
	s_movk_i32 s3, 0x100
	s_add_i32 s23, s23, 0
	s_add_i32 s39, s38, 0
	v_bitop3_b32 v18, v20, s7, v22 bitop3:0xde
	s_lshl_b32 s7, s22, 7
	v_lshl_add_u32 v140, v9, 1, v0
	v_lshlrev_b32_e32 v0, 14, v4
	v_cmp_gt_i32_e64 s[4:5], s3, v132
	v_readlane_b32 s3, v254, 40
	s_cmpk_lt_u32 s6, 0x100
	v_and_b32_e32 v0, 0xffff8000, v0
	s_waitcnt vmcnt(6)
	s_cselect_b64 s[50:51], -1, 0
	s_add_i32 s6, s3, s38
	v_lshl_add_u32 v0, v5, 11, v0
	v_and_b32_e32 v1, 1, v4
	v_bitop3_b32 v166, s7, v20, v22 bitop3:0xf6
	s_add_i32 s23, s23, 0x20400
	v_add_u32_e32 v168, s6, v21
	s_add_i32 s39, s39, 0x20200
	v_lshl_or_b32 v0, v1, 6, v0
	v_readlane_b32 s6, v252, 59
	s_mov_b32 s90, 0
	v_lshl_add_u32 v164, v132, 2, s3
	v_lshl_add_u32 v167, v19, 2, s23
	v_add_u32_e32 v169, s39, v21
	v_or_b32_e32 v170, s22, v19
	v_mov_b32_e32 v141, v193
	v_lshl_add_u32 v142, v6, 1, v0
	v_mov_b32_e32 v143, v193
	v_add_u32_e32 v171, 0, v18
	s_mov_b32 s52, s6
	v_readlane_b32 s53, v252, 58
	s_barrier
	v_readlane_b32 s7, v252, 60
	s_branch .LBB0_163

; #define LAS __attribute__((address_space(3)))
; __device__ __forceinline__ void sb_attn_wave(const bf16_t* __restrict__ P, const bf16_t* __restrict__ KHp, const bf16_t* __restrict__ Vt, bf16_t* __restrict__ mixed, int gw, int NGW, int lane, LAS unsigned char* wl) {
;     constexpr int NUNITS = NBATCH * 8 * 128;
;     const int r32 = lane & 31, hi = lane >> 5;
;     const int pi = (r32 & 19) | ((r32 & 4) << 1) | ((r32 & 8) >> 1);
;     const int lr = lane >> 3, lp = lane & 7;
;     LAS unsigned char* kl = wl; LAS unsigned char* vl = wl + SB_TILE;
;     const int wofs = lr * SB_PITCH + lp * 16;
;     const int kro = pi * SB_PITCH + hi * 16;
;     const int vro = r32 * SB_PITCH + hi * 16;
;     int u = gw; if (u >= NUNITS) return;
;     size_t tok0; int q0, h, kt; const bf16_t* kg; const bf16_t* vg;
;     bf16x8 qf[4]; u32x4 ks[8], vs[8];
;     ...
;     SB_UNIT_SETUP(u);
.LBB0_404:
	s_cmp_ge_i32 s52, s28
	s_cselect_b64 s[4:5], -1, 0
	s_and_b64 s[0:1], s[4:5], s[0:1]
	s_andn2_b64 vcc, exec, s[0:1]
	s_cbranch_vccnz .LBB0_471
	v_readlane_b32 s0, v253, 50
	v_mov_b32_e32 v145, v223
	v_readlane_b32 s1, v253, 51
	s_andn2_b64 vcc, exec, s[0:1]
	v_and_b32_e32 v147, 63, v145
	s_mov_b32 s101, 0
	s_cbranch_vccnz .LBB0_420
	v_readlane_b32 s100, v254, 2
	s_nop 0
	s_bitcmp0_b32 s100, 2
	s_cbranch_scc1 .LBB0_420
.Lmix_attn_entry:
	v_lshlrev_b32_e32 v3, 1, v147
	s_waitcnt vmcnt(0)
	v_lshrrev_b32_e32 v4, 1, v145
	v_and_b32_e32 v2, 19, v145
	v_and_b32_e32 v3, 8, v3
	v_and_b32_e32 v4, 4, v4
	v_or3_b32 v3, v2, v3, v4
	v_lshlrev_b32_e32 v2, 4, v145
	s_waitcnt lgkmcnt(0)
	v_lshrrev_b32_e32 v1, 5, v147
	v_lshrrev_b32_e32 v4, 3, v147
	v_and_b32_e32 v2, 0x70, v2
	s_movk_i32 s1, 0x90
	v_readlane_b32 s0, v253, 52
	v_lshlrev_b32_e32 v0, 4, v1
	v_mad_u32_u24 v5, v4, s1, v2
	v_lshlrev_b32_e32 v146, 3, v1
	v_lshlrev_b32_e32 v192, 7, v4
	v_lshlrev_b32_e32 v4, 2, v1
	v_mov_b32_e32 v1, s0
	v_mad_u32_u24 v10, v3, s1, v1
	v_lshl_add_u64 v[6:7], s[20:21], 0, v[192:193]
	v_mov_b32_e32 v3, v193
	v_lshl_add_u64 v[148:149], v[6:7], 0, v[2:3]
	v_lshl_add_u64 v[6:7], s[18:19], 0, v[192:193]
	v_and_b32_e32 v144, 31, v145
	v_lshl_add_u64 v[150:151], v[6:7], 0, v[2:3]
	v_and_b32_e32 v6, 64, v228
	v_readlane_b32 s4, v253, 61
	v_mad_u32_u24 v11, v144, s1, v1
	v_xor_b32_e32 v1, 32, v228
	v_add_u32_e32 v6, 64, v6
	v_readlane_b32 s5, v253, 62
	v_cmp_lt_i32_e32 vcc, v1, v6
	v_readlane_b32 s8, v254, 43
	v_lshl_add_u64 v[6:7], s[4:5], 0, v[192:193]
	v_readlane_b32 s4, v253, 63
	v_readlane_b32 s5, v254, 0
	v_readlane_b32 s1, v253, 54
	v_readlane_b32 s9, v254, 44
	v_lshl_add_u64 v[8:9], s[4:5], 0, v[192:193]
	s_mov_b32 s4, s8
	v_lshl_add_u64 v[154:155], v[8:9], 0, v[2:3]
	v_writelane_b32 v254, s4, 43
	v_or_b32_e32 v8, s1, v144
	v_readlane_b32 s1, v253, 57
	v_writelane_b32 v254, s5, 44
	v_readlane_b32 s4, v253, 59
	v_mov_b32_e32 v9, s1
	v_cndmask_b32_e32 v1, v228, v1, vcc
	v_lshlrev_b64 v[8:9], 12, v[8:9]
	v_readlane_b32 s5, v253, 60
	v_lshlrev_b32_e32 v156, 2, v1
	s_mov_b32 s9, s13
	v_lshl_add_u64 v[8:9], s[4:5], 0, v[8:9]
	v_mov_b32_e32 v1, v193
	v_lshl_add_u64 v[152:153], v[6:7], 0, v[2:3]
	v_lshl_add_u64 v[2:3], v[154:155], 0, s[8:9]
	v_lshl_add_u64 v[8:9], v[8:9], 0, v[0:1]
	s_movk_i32 s1, 0x1000
	global_load_dwordx4 v[64:67], v[8:9], off
	global_load_dwordx4 v[68:71], v[8:9], off offset:32
	s_waitcnt lgkmcnt(0)
	global_load_dwordx4 v[72:75], v[8:9], off offset:64
	global_load_dwordx4 v[76:79], v[8:9], off offset:96
	global_load_dwordx4 v[80:83], v[2:3], off
	global_load_dwordx4 v[84:87], v[2:3], off offset:1024
	global_load_dwordx4 v[88:91], v[2:3], off offset:2048
	global_load_dwordx4 v[92:95], v[2:3], off offset:3072
	v_add_co_u32_e32 v2, vcc, s1, v2
	v_lshl_add_u64 v[6:7], v[152:153], 0, s[8:9]
	s_nop 0
	v_addc_co_u32_e32 v3, vcc, 0, v3, vcc
	global_load_dwordx4 v[96:99], v[2:3], off
	global_load_dwordx4 v[100:103], v[2:3], off offset:1024
	global_load_dwordx4 v[104:107], v[2:3], off offset:2048
	global_load_dwordx4 v[108:111], v[2:3], off offset:3072
	global_load_dwordx4 v[112:115], v[6:7], off
	global_load_dwordx4 v[116:119], v[6:7], off offset:1024
	global_load_dwordx4 v[120:123], v[6:7], off offset:2048
	global_load_dwordx4 v[124:127], v[6:7], off offset:3072
	v_add_co_u32_e32 v2, vcc, 0x1000, v6
	v_add_u32_e32 v157, s0, v5
	s_nop 0
	v_addc_co_u32_e32 v3, vcc, 0, v7, vcc
	global_load_dwordx4 v[128:131], v[2:3], off
	global_load_dwordx4 v[132:135], v[2:3], off offset:1024
	global_load_dwordx4 v[136:139], v[2:3], off offset:2048
	global_load_dwordx4 v[140:143], v[2:3], off offset:3072
	v_readlane_b32 s0, v253, 55
	v_cmp_gt_u32_e64 s[6:7], 32, v147
	v_lshlrev_b32_e32 v192, 1, v4
	v_add_u32_e32 v158, v10, v0
	v_add_u32_e32 v159, v11, v0
	v_readlane_b32 s38, v254, 1
	v_readlane_b32 s39, v253, 58
	v_readlane_b32 s48, v253, 53
	v_readlane_b32 s1, v253, 56
	v_readlane_b32 s49, v254, 2
	s_branch .LBB0_408

; __device__ __forceinline__ void convpool_unit(const bf16_t* __restrict__ P, bf16_t* __restrict__ mixed, const float* convw, int uu, int lane) {
;     const int c8 = (lane & 31) * 8, t0 = uu * 16 + (lane >> 5) * 8, s0 = t0 & (SEQ - 1);
;     {
;         float w0[8], w1[8], w2[8], p2[8], p1[8];
;         const bf16_t* pc = P + 1280 + c8; const bf16_t* pu = P + 1536 + c8; const bf16_t* pb = P + 1024 + c8;
;         {
;             const bool hv = (s0 >= 2);
;             const size_t tm2 = hv ? (size_t)(t0 - 2) : (size_t)t0, tm1 = hv ? (size_t)(t0 - 1) : (size_t)t0;
;             const u32x4 a2 = *(const u32x4*)(pc + tm2 * PW), b2 = *(const u32x4*)(pu + tm2 * PW), a1 = *(const u32x4*)(pc + tm1 * PW), b1 = *(const u32x4*)(pu + tm1 * PW);
;             float x[8], y[8];
;             up8(a2, x); up8(b2, y);
; #pragma unroll
;             for (int i = 0; i < 8; ++i) p2[i] = hv ? x[i] * y[i] : 0.f;
;             up8(a1, x); up8(b1, y);
; #pragma unroll
;             for (int i = 0; i < 8; ++i) p1[i] = hv ? x[i] * y[i] : 0.f;
; #pragma unroll
;             for (int i = 0; i < 8; ++i) { w0[i] = convw[c8 + i]; w1[i] = convw[256 + c8 + i]; w2[i] = convw[512 + c8 + i]; }
;         }
.LBB0_420:
	s_cmp_eq_u32 s101, 1
	s_cbranch_scc1 .Lmix_done
	v_readlane_b32 s0, v254, 3
	v_readlane_b32 s1, v254, 4
	s_andn2_b64 vcc, exec, s[0:1]
	v_readlane_b32 s12, v254, 48
	s_cbranch_vccnz .Lmix_cp_done
	s_waitcnt vmcnt(0)
	v_lshlrev_b32_e32 v16, 3, v147
	v_and_b32_e32 v17, 0xf8, v16
	v_readlane_b32 s0, v254, 58
	v_lshlrev_b32_e32 v12, 2, v17
	v_lshlrev_b32_e32 v0, 5, v147
	v_readlane_b32 s1, v254, 59
	v_or_b32_e32 v18, 0x400, v0
	v_or_b32_e32 v19, 0x404, v0
	v_or_b32_e32 v20, 0x408, v0
	v_or_b32_e32 v21, 0x40c, v0
	v_or_b32_e32 v22, 0x410, v0
	v_or_b32_e32 v23, 0x414, v0
	v_or_b32_e32 v24, 0x418, v0
	v_or_b32_e32 v25, 0x41c, v0
	s_waitcnt lgkmcnt(0)
	global_load_dwordx4 v[0:3], v12, s[0:1] offset:16
	global_load_dwordx4 v[4:7], v12, s[0:1]
	global_load_dwordx4 v[8:11], v12, s[0:1] offset:2064
	s_nop 0
	global_load_dwordx4 v[12:15], v12, s[0:1] offset:2048
	s_nop 0
	global_load_dword v112, v18, s[0:1]
	global_load_dword v113, v19, s[0:1]
	global_load_dword v114, v20, s[0:1]
	global_load_dword v115, v21, s[0:1]
	global_load_dword v116, v22, s[0:1]
	global_load_dword v117, v23, s[0:1]
	global_load_dword v118, v24, s[0:1]
	global_load_dword v119, v25, s[0:1]
	v_readlane_b32 s0, v254, 5
	v_lshlrev_b32_e32 v192, 1, v17
	v_readlane_b32 s1, v254, 6
	v_lshrrev_b32_e32 v18, 2, v145
	v_bfe_u32 v16, v16, 6, 2
	v_lshl_add_u64 v[120:121], s[0:1], 0, v[192:193]
	v_readlane_b32 s0, v254, 7
	v_readlane_b32 s1, v254, 8
	v_and_b32_e32 v18, 8, v18
	v_lshlrev_b32_e64 v160, v16, 2
	v_lshl_add_u64 v[122:123], s[0:1], 0, v[192:193]
	v_readlane_b32 s0, v254, 9
	v_readlane_b32 s1, v254, 10
	v_lshl_add_u64 v[128:129], s[64:65], 0, v[192:193]
	s_waitcnt lgkmcnt(5)
	v_sub_u32_e32 v161, 0, v160
	v_lshl_add_u64 v[124:125], s[0:1], 0, v[192:193]
	v_readlane_b32 s0, v254, 11
	v_readlane_b32 s1, v254, 12
	v_readlane_b32 s6, v254, 2
	s_nop 0
	v_lshl_add_u64 v[126:127], s[0:1], 0, v[192:193]
	v_readlane_b32 s0, v254, 39
	s_nop 1
	v_add_u32_e32 v130, s0, v18
	s_branch .LBB0_423

; __global__ void __launch_bounds__(512, 2) fwd_kernel(Args a) {
;     ...
;                 if (STEP_ON) { LANE_VARS; for (int rep = 0; rep < REP_MIX; ++rep) {
;                     sb_attn_wave(PROJ, (const bf16_t*)(ws + WS_KH), VT, MIX, gw, NGW, lane, lds + wave * SB_WAVE_LDS);
;                     for (int u = gw; u < MTOK / 16; u += NGW) convpool_unit(PROJ, MIX, a.in[12] + (size_t)l * 768, u, lane);
;                 } }
.Lmix_cp_done:
	s_cmp_eq_u32 s101, 0
	s_cbranch_scc0 .LBB0_471
	v_readlane_b32 s100, v254, 2
	s_nop 0
	s_bitcmp0_b32 s100, 2
	s_cbranch_scc0 .LBB0_471
	s_mov_b32 s101, 1
	v_mov_b32_e32 v145, v223
	v_and_b32_e32 v147, 63, v145
	s_branch .Lmix_attn_entry
.Lmix_done:
	v_readlane_b32 s12, v254, 48
	s_branch .LBB0_471
